# post_rows loop rewritten: invariant loads hoisted, next-row loads prefetched, DPP reductions
# speedup vs baseline: 1.0179x; 1.0179x over previous
.LBB0_1201:
	global_load_dwordx4 v[0:3], v[16:17], off offset:16
	global_load_dwordx4 v[4:7], v[16:17], off
	global_load_dwordx4 v[8:11], v[18:19], off offset:16
	global_load_dwordx4 v[12:15], v[18:19], off
	v_lshl_add_u64 v[38:39], v[22:23], 0, s[48:49]
	v_lshl_add_u64 v[42:43], v[38:39], 0, s[50:51]
	v_add_co_u32_e32 v38, vcc, 0x15000000, v38
	s_add_i32 s6, s7, s9
	v_lshl_add_u64 v[26:27], v[24:25], 0, s[48:49]
	v_lshl_add_u64 v[40:41], v[20:21], 0, s[48:49]
	v_addc_co_u32_e32 v39, vcc, 0, v39, vcc
	s_ashr_i32 s18, s6, 31
	global_load_dwordx4 v[34:37], v[26:27], off
	global_load_dword v28, v[40:41], off
	s_nop 0
	global_load_dwordx4 v[38:41], v[38:39], off
	s_nop 0
	global_load_dwordx4 v[42:45], v[42:43], off offset:16
	s_lshr_b32 s18, s18, 21
	s_add_i32 s18, s6, s18
	s_ashr_i32 s21, s18, 11
	s_and_b32 s18, s18, 0xfffff800
	v_lshl_or_b32 v50, s21, 3, v29
	s_sub_i32 s20, s6, s18
	v_ashrrev_i32_e32 v51, 31, v50
	s_ashr_i32 s21, s20, 31
	v_lshlrev_b64 v[50:51], 11, v[50:51]
	v_mov_b64_e32 v[46:47], s[2:3]
	v_lshl_add_u64 v[50:51], v[50:51], 0, s[20:21]
	v_mad_u64_u32 v[46:47], s[20:21], v50, s95, v[46:47]
	v_mad_i32_i24 v47, v51, s95, v47
	v_lshl_add_u64 v[46:47], v[46:47], 0, v[48:49]
	s_mov_b32 s6, 0xf000000
	v_add_co_u32_e32 v46, vcc, s6, v46
	s_add_i32 s9, s9, s74
	s_nop 0
	v_addc_co_u32_e32 v47, vcc, 0, v47, vcc
	global_load_dwordx4 v[50:53], v[46:47], off offset:640
	v_lshl_add_u64 v[20:21], v[20:21], 0, s[96:97]
	v_lshl_add_u64 v[22:23], v[22:23], 0, s[46:47]
	v_lshl_add_u64 v[24:25], v[24:25], 0, s[46:47]
	s_waitcnt vmcnt(0)
.Lpost_loop:
	v_mov_b64_e32 v[68:69], v[34:35]
	v_mov_b64_e32 v[70:71], v[36:37]
	v_mov_b32_e32 v72, v28
	v_mov_b64_e32 v[74:75], v[38:39]
	v_mov_b64_e32 v[76:77], v[40:41]
	v_mov_b64_e32 v[78:79], v[42:43]
	v_mov_b64_e32 v[80:81], v[44:45]
	v_mov_b64_e32 v[82:83], v[50:51]
	v_mov_b64_e32 v[84:85], v[52:53]
	v_mov_b64_e32 v[86:87], v[26:27]
	s_cmpk_lt_i32 s9, 0x800
	s_cbranch_scc0 .Lpost_last
	v_lshl_add_u64 v[38:39], v[22:23], 0, s[48:49]
	v_lshl_add_u64 v[42:43], v[38:39], 0, s[50:51]
	v_add_co_u32_e32 v38, vcc, 0x15000000, v38
	s_add_i32 s6, s7, s9
	v_lshl_add_u64 v[26:27], v[24:25], 0, s[48:49]
	v_lshl_add_u64 v[40:41], v[20:21], 0, s[48:49]
	v_addc_co_u32_e32 v39, vcc, 0, v39, vcc
	s_ashr_i32 s18, s6, 31
	global_load_dwordx4 v[34:37], v[26:27], off
	global_load_dword v28, v[40:41], off
	s_nop 0
	global_load_dwordx4 v[38:41], v[38:39], off
	s_nop 0
	global_load_dwordx4 v[42:45], v[42:43], off offset:16
	s_lshr_b32 s18, s18, 21
	s_add_i32 s18, s6, s18
	s_ashr_i32 s21, s18, 11
	s_and_b32 s18, s18, 0xfffff800
	v_lshl_or_b32 v50, s21, 3, v29
	s_sub_i32 s20, s6, s18
	v_ashrrev_i32_e32 v51, 31, v50
	s_ashr_i32 s21, s20, 31
	v_lshlrev_b64 v[50:51], 11, v[50:51]
	v_mov_b64_e32 v[46:47], s[2:3]
	v_lshl_add_u64 v[50:51], v[50:51], 0, s[20:21]
	v_mad_u64_u32 v[46:47], s[20:21], v50, s95, v[46:47]
	v_mad_i32_i24 v47, v51, s95, v47
	v_lshl_add_u64 v[46:47], v[46:47], 0, v[48:49]
	s_mov_b32 s6, 0xf000000
	v_add_co_u32_e32 v46, vcc, s6, v46
	s_add_i32 s9, s9, s74
	s_nop 0
	v_addc_co_u32_e32 v47, vcc, 0, v47, vcc
	global_load_dwordx4 v[50:53], v[46:47], off offset:640
	v_lshl_add_u64 v[20:21], v[20:21], 0, s[96:97]
	v_lshl_add_u64 v[22:23], v[22:23], 0, s[46:47]
	v_lshl_add_u64 v[24:25], v[24:25], 0, s[46:47]
	v_add_f32_e32 v33, 0, v74
	v_add_f32_e32 v33, v75, v33
	v_add_f32_e32 v33, v76, v33
	v_add_f32_e32 v33, v77, v33
	v_add_f32_e32 v33, v78, v33
	v_add_f32_e32 v33, v79, v33
	v_add_f32_e32 v33, v80, v33
	v_add_f32_e32 v33, v81, v33
	s_nop 1
	v_add_f32_dpp v33, v33, v33 quad_perm:[1,0,3,2] row_mask:0xf bank_mask:0xf bound_ctrl:1
	s_nop 1
	v_add_f32_dpp v33, v33, v33 quad_perm:[2,3,0,1] row_mask:0xf bank_mask:0xf bound_ctrl:1
	s_nop 1
	v_add_f32_dpp v33, v33, v33 row_half_mirror row_mask:0xf bank_mask:0xf bound_ctrl:1
	v_mul_f32_e32 v54, 0x3c800000, v33
	v_pk_add_f32 v[74:75], v[74:75], v[54:55] op_sel_hi:[1,0] neg_lo:[0,1] neg_hi:[0,1]
	v_pk_add_f32 v[76:77], v[76:77], v[54:55] op_sel_hi:[1,0] neg_lo:[0,1] neg_hi:[0,1]
	v_pk_mul_f32 v[66:67], v[74:75], v[74:75]
	v_pk_mul_f32 v[64:65], v[76:77], v[76:77]
	v_add_f32_e32 v33, v66, v67
	v_pk_add_f32 v[78:79], v[78:79], v[54:55] op_sel_hi:[1,0] neg_lo:[0,1] neg_hi:[0,1]
	v_add_f32_e32 v33, v64, v33
	v_pk_mul_f32 v[62:63], v[78:79], v[78:79]
	v_add_f32_e32 v33, v65, v33
	v_pk_add_f32 v[80:81], v[80:81], v[54:55] op_sel_hi:[1,0] neg_lo:[0,1] neg_hi:[0,1]
	v_add_f32_e32 v33, v62, v33
	v_pk_mul_f32 v[54:55], v[80:81], v[80:81]
	v_add_f32_e32 v33, v63, v33
	v_add_f32_e32 v33, v54, v33
	v_add_f32_e32 v33, v55, v33
	s_nop 1
	v_add_f32_dpp v33, v33, v33 quad_perm:[1,0,3,2] row_mask:0xf bank_mask:0xf bound_ctrl:1
	s_nop 1
	v_add_f32_dpp v33, v33, v33 quad_perm:[2,3,0,1] row_mask:0xf bank_mask:0xf bound_ctrl:1
	s_nop 1
	v_add_f32_dpp v33, v33, v33 row_half_mirror row_mask:0xf bank_mask:0xf bound_ctrl:1
	v_mov_b32_e32 v54, 0x3a27c5ac
	v_fmamk_f32 v33, v33, 0x3c800000, v54
	v_mul_f32_e32 v54, 0x4b800000, v33
	v_cmp_gt_f32_e32 vcc, s75, v33
	s_nop 1
	v_cndmask_b32_e32 v33, v33, v54, vcc
	v_rsq_f32_e32 v33, v33
	s_nop 0
	v_mul_f32_e32 v54, 0x45800000, v33
	v_cndmask_b32_e32 v54, v33, v54, vcc
	v_pk_mul_f32 v[74:75], v[74:75], v[54:55] op_sel_hi:[1,0]
	v_pk_mul_f32 v[76:77], v[76:77], v[54:55] op_sel_hi:[1,0]
	v_pk_mul_f32 v[78:79], v[78:79], v[54:55] op_sel_hi:[1,0]
	v_pk_mul_f32 v[80:81], v[80:81], v[54:55] op_sel_hi:[1,0]
	v_pk_fma_f32 v[74:75], v[4:5], v[74:75], v[12:13]
	v_pk_fma_f32 v[76:77], v[6:7], v[76:77], v[14:15]
	v_pk_fma_f32 v[78:79], v[0:1], v[78:79], v[8:9]
	v_pk_fma_f32 v[80:81], v[2:3], v[80:81], v[10:11]
	v_lshlrev_b32_e32 v60, 16, v82
	v_and_b32_e32 v61, 0xffff0000, v82
	v_lshlrev_b32_e32 v62, 16, v83
	v_and_b32_e32 v63, 0xffff0000, v83
	v_lshlrev_b32_e32 v58, 16, v84
	v_and_b32_e32 v59, 0xffff0000, v84
	v_lshlrev_b32_e32 v64, 16, v85
	v_and_b32_e32 v65, 0xffff0000, v85
	v_pk_fma_f32 v[74:75], v[72:73], v[60:61], v[74:75] op_sel_hi:[0,1,1]
	v_pk_fma_f32 v[76:77], v[72:73], v[62:63], v[76:77] op_sel_hi:[0,1,1]
	v_pk_fma_f32 v[78:79], v[72:73], v[58:59], v[78:79] op_sel_hi:[0,1,1]
	v_pk_fma_f32 v[80:81], v[72:73], v[64:65], v[80:81] op_sel_hi:[0,1,1]
	v_lshlrev_b32_e32 v56, 16, v68
	v_and_b32_e32 v57, 0xffff0000, v68
	v_lshlrev_b32_e32 v60, 16, v69
	v_and_b32_e32 v61, 0xffff0000, v69
	v_lshlrev_b32_e32 v62, 16, v70
	v_and_b32_e32 v63, 0xffff0000, v70
	v_lshlrev_b32_e32 v64, 16, v71
	v_and_b32_e32 v65, 0xffff0000, v71
	v_pk_mul_f32 v[74:75], v[74:75], v[56:57]
	v_pk_mul_f32 v[76:77], v[76:77], v[60:61]
	v_pk_mul_f32 v[78:79], v[78:79], v[62:63]
	v_pk_mul_f32 v[80:81], v[80:81], v[64:65]
	v_cvt_pk_bf16_f32 v88, v74, v75
	v_cvt_pk_bf16_f32 v89, v76, v77
	v_cvt_pk_bf16_f32 v90, v78, v79
	v_cvt_pk_bf16_f32 v91, v80, v81
	global_store_dwordx4 v[86:87], v[88:91], off
	s_nop 1
	s_waitcnt vmcnt(1)
	s_branch .Lpost_loop
.Lpost_last:
	v_add_f32_e32 v33, 0, v74
	v_add_f32_e32 v33, v75, v33
	v_add_f32_e32 v33, v76, v33
	v_add_f32_e32 v33, v77, v33
	v_add_f32_e32 v33, v78, v33
	v_add_f32_e32 v33, v79, v33
	v_add_f32_e32 v33, v80, v33
	v_add_f32_e32 v33, v81, v33
	s_nop 1
	v_add_f32_dpp v33, v33, v33 quad_perm:[1,0,3,2] row_mask:0xf bank_mask:0xf bound_ctrl:1
	s_nop 1
	v_add_f32_dpp v33, v33, v33 quad_perm:[2,3,0,1] row_mask:0xf bank_mask:0xf bound_ctrl:1
	s_nop 1
	v_add_f32_dpp v33, v33, v33 row_half_mirror row_mask:0xf bank_mask:0xf bound_ctrl:1
	v_mul_f32_e32 v54, 0x3c800000, v33
	v_pk_add_f32 v[74:75], v[74:75], v[54:55] op_sel_hi:[1,0] neg_lo:[0,1] neg_hi:[0,1]
	v_pk_add_f32 v[76:77], v[76:77], v[54:55] op_sel_hi:[1,0] neg_lo:[0,1] neg_hi:[0,1]
	v_pk_mul_f32 v[66:67], v[74:75], v[74:75]
	v_pk_mul_f32 v[64:65], v[76:77], v[76:77]
	v_add_f32_e32 v33, v66, v67
	v_pk_add_f32 v[78:79], v[78:79], v[54:55] op_sel_hi:[1,0] neg_lo:[0,1] neg_hi:[0,1]
	v_add_f32_e32 v33, v64, v33
	v_pk_mul_f32 v[62:63], v[78:79], v[78:79]
	v_add_f32_e32 v33, v65, v33
	v_pk_add_f32 v[80:81], v[80:81], v[54:55] op_sel_hi:[1,0] neg_lo:[0,1] neg_hi:[0,1]
	v_add_f32_e32 v33, v62, v33
	v_pk_mul_f32 v[54:55], v[80:81], v[80:81]
	v_add_f32_e32 v33, v63, v33
	v_add_f32_e32 v33, v54, v33
	v_add_f32_e32 v33, v55, v33
	s_nop 1
	v_add_f32_dpp v33, v33, v33 quad_perm:[1,0,3,2] row_mask:0xf bank_mask:0xf bound_ctrl:1
	s_nop 1
	v_add_f32_dpp v33, v33, v33 quad_perm:[2,3,0,1] row_mask:0xf bank_mask:0xf bound_ctrl:1
	s_nop 1
	v_add_f32_dpp v33, v33, v33 row_half_mirror row_mask:0xf bank_mask:0xf bound_ctrl:1
	v_mov_b32_e32 v54, 0x3a27c5ac
	v_fmamk_f32 v33, v33, 0x3c800000, v54
	v_mul_f32_e32 v54, 0x4b800000, v33
	v_cmp_gt_f32_e32 vcc, s75, v33
	s_nop 1
	v_cndmask_b32_e32 v33, v33, v54, vcc
	v_rsq_f32_e32 v33, v33
	s_nop 0
	v_mul_f32_e32 v54, 0x45800000, v33
	v_cndmask_b32_e32 v54, v33, v54, vcc
	v_pk_mul_f32 v[74:75], v[74:75], v[54:55] op_sel_hi:[1,0]
	v_pk_mul_f32 v[76:77], v[76:77], v[54:55] op_sel_hi:[1,0]
	v_pk_mul_f32 v[78:79], v[78:79], v[54:55] op_sel_hi:[1,0]
	v_pk_mul_f32 v[80:81], v[80:81], v[54:55] op_sel_hi:[1,0]
	v_pk_fma_f32 v[74:75], v[4:5], v[74:75], v[12:13]
	v_pk_fma_f32 v[76:77], v[6:7], v[76:77], v[14:15]
	v_pk_fma_f32 v[78:79], v[0:1], v[78:79], v[8:9]
	v_pk_fma_f32 v[80:81], v[2:3], v[80:81], v[10:11]
	v_lshlrev_b32_e32 v60, 16, v82
	v_and_b32_e32 v61, 0xffff0000, v82
	v_lshlrev_b32_e32 v62, 16, v83
	v_and_b32_e32 v63, 0xffff0000, v83
	v_lshlrev_b32_e32 v58, 16, v84
	v_and_b32_e32 v59, 0xffff0000, v84
	v_lshlrev_b32_e32 v64, 16, v85
	v_and_b32_e32 v65, 0xffff0000, v85
	v_pk_fma_f32 v[74:75], v[72:73], v[60:61], v[74:75] op_sel_hi:[0,1,1]
	v_pk_fma_f32 v[76:77], v[72:73], v[62:63], v[76:77] op_sel_hi:[0,1,1]
	v_pk_fma_f32 v[78:79], v[72:73], v[58:59], v[78:79] op_sel_hi:[0,1,1]
	v_pk_fma_f32 v[80:81], v[72:73], v[64:65], v[80:81] op_sel_hi:[0,1,1]
	v_lshlrev_b32_e32 v56, 16, v68
	v_and_b32_e32 v57, 0xffff0000, v68
	v_lshlrev_b32_e32 v60, 16, v69
	v_and_b32_e32 v61, 0xffff0000, v69
	v_lshlrev_b32_e32 v62, 16, v70
	v_and_b32_e32 v63, 0xffff0000, v70
	v_lshlrev_b32_e32 v64, 16, v71
	v_and_b32_e32 v65, 0xffff0000, v71
	v_pk_mul_f32 v[74:75], v[74:75], v[56:57]
	v_pk_mul_f32 v[76:77], v[76:77], v[60:61]
	v_pk_mul_f32 v[78:79], v[78:79], v[62:63]
	v_pk_mul_f32 v[80:81], v[80:81], v[64:65]
	v_cvt_pk_bf16_f32 v88, v74, v75
	v_cvt_pk_bf16_f32 v89, v76, v77
	v_cvt_pk_bf16_f32 v90, v78, v79
	v_cvt_pk_bf16_f32 v91, v80, v81
	global_store_dwordx4 v[86:87], v[88:91], off
	s_nop 1
.Lpost_done:
.LBB0_1202:
	s_mov_b64 s[42:43], -1
